# v15 with the grid-barrier poll interval shortened (s_sleep 2 to s_sleep 1 at the 10 barrier sites)
# speedup vs baseline: 1.0066x; 1.0052x over previous
; __global__ void __launch_bounds__(512, 2) fwd_megakernel(Params p) {
;     ...
;     grid.sync();
.Lgb1_poll:
	global_load_dword v1, v0, s[8:9] sc1
	s_waitcnt vmcnt(0)
	v_readfirstlane_b32 s11, v1
	s_nop 3
	s_cmp_ge_u32 s11, s10
	s_cbranch_scc1 .Lgb1_done
	s_sleep 1
	s_branch .Lgb1_poll
